# transposed-weight stores marked non-temporal
# baseline (speedup 1.0000x reference)
; __device__ __forceinline__ void transpose_item64(const float* __restrict__ W, int K, int N, bf16* __restrict__ WT, int mode, float* scr, int item, int lane) {
;     const int nblk = (N + 63) >> 6, kb = item / nblk, nb = item - kb * nblk, k0 = kb << 6, n0 = nb << 6;
;     const int lr = lane >> 4, lc = (lane & 15) << 2;
;     const bool ok = (n0 + lc) < N;
; #pragma unroll
;     for (int i = 0; i < 16; ++i) {
;         const int kk = 4 * i + lr; f32x4 v = {0.f, 0.f, 0.f, 0.f};
;         if (ok) v = __builtin_nontemporal_load((const f32x4*)(W + (size_t)(k0 + kk) * N + n0 + lc));
;         float* s = scr + kk * 65 + lc; s[0] = v.x; s[1] = v.y; s[2] = v.z; s[3] = v.w;
;     }
.Ltr_ld:
	global_load_dwordx4 v[64:67], v[4:5], off nt
	v_lshl_add_u64 v[4:5], v[4:5], 0, s[16:17]
	global_load_dwordx4 v[68:71], v[4:5], off nt
	v_lshl_add_u64 v[4:5], v[4:5], 0, s[16:17]
	global_load_dwordx4 v[72:75], v[4:5], off nt
	v_lshl_add_u64 v[4:5], v[4:5], 0, s[16:17]
	global_load_dwordx4 v[76:79], v[4:5], off nt
	v_lshl_add_u64 v[4:5], v[4:5], 0, s[16:17]
	global_load_dwordx4 v[80:83], v[4:5], off nt
	v_lshl_add_u64 v[4:5], v[4:5], 0, s[16:17]
	global_load_dwordx4 v[84:87], v[4:5], off nt
	v_lshl_add_u64 v[4:5], v[4:5], 0, s[16:17]
	global_load_dwordx4 v[88:91], v[4:5], off nt
	v_lshl_add_u64 v[4:5], v[4:5], 0, s[16:17]
	global_load_dwordx4 v[92:95], v[4:5], off nt
	v_lshl_add_u64 v[4:5], v[4:5], 0, s[16:17]
	global_load_dwordx4 v[96:99], v[4:5], off nt
	v_lshl_add_u64 v[4:5], v[4:5], 0, s[16:17]
	global_load_dwordx4 v[100:103], v[4:5], off nt
	v_lshl_add_u64 v[4:5], v[4:5], 0, s[16:17]
	global_load_dwordx4 v[104:107], v[4:5], off nt
	v_lshl_add_u64 v[4:5], v[4:5], 0, s[16:17]
	global_load_dwordx4 v[108:111], v[4:5], off nt
	v_lshl_add_u64 v[4:5], v[4:5], 0, s[16:17]
	global_load_dwordx4 v[112:115], v[4:5], off nt
	v_lshl_add_u64 v[4:5], v[4:5], 0, s[16:17]
	global_load_dwordx4 v[116:119], v[4:5], off nt
	v_lshl_add_u64 v[4:5], v[4:5], 0, s[16:17]
	global_load_dwordx4 v[120:123], v[4:5], off nt
	v_lshl_add_u64 v[4:5], v[4:5], 0, s[16:17]
	global_load_dwordx4 v[124:127], v[4:5], off nt
	s_mov_b64 exec, -1
	v_mad_u32_u24 v2, v15, s7, v16
	v_lshl_add_u64 v[6:7], s[8:9], 0, v[2:3]
	s_waitcnt vmcnt(15)
	ds_write_b32 v10, v64 offset:0
	ds_write_b32 v10, v65 offset:4
	ds_write_b32 v10, v66 offset:8
	ds_write_b32 v10, v67 offset:12
	s_waitcnt vmcnt(14)
	ds_write_b32 v10, v68 offset:1040
	ds_write_b32 v10, v69 offset:1044
	ds_write_b32 v10, v70 offset:1048
	ds_write_b32 v10, v71 offset:1052
	s_waitcnt vmcnt(13)
	ds_write_b32 v10, v72 offset:2080
	ds_write_b32 v10, v73 offset:2084
	ds_write_b32 v10, v74 offset:2088
	ds_write_b32 v10, v75 offset:2092
	s_waitcnt vmcnt(12)
	ds_write_b32 v10, v76 offset:3120
	ds_write_b32 v10, v77 offset:3124
	ds_write_b32 v10, v78 offset:3128
	ds_write_b32 v10, v79 offset:3132
	s_waitcnt vmcnt(11)
	ds_write_b32 v10, v80 offset:4160
	ds_write_b32 v10, v81 offset:4164
	ds_write_b32 v10, v82 offset:4168
	ds_write_b32 v10, v83 offset:4172
	s_waitcnt vmcnt(10)
	ds_write_b32 v10, v84 offset:5200
	ds_write_b32 v10, v85 offset:5204
	ds_write_b32 v10, v86 offset:5208
	ds_write_b32 v10, v87 offset:5212
	s_waitcnt vmcnt(9)
	ds_write_b32 v10, v88 offset:6240
	ds_write_b32 v10, v89 offset:6244
	ds_write_b32 v10, v90 offset:6248
	ds_write_b32 v10, v91 offset:6252
	s_waitcnt vmcnt(8)
	ds_write_b32 v10, v92 offset:7280
	ds_write_b32 v10, v93 offset:7284
	ds_write_b32 v10, v94 offset:7288
	ds_write_b32 v10, v95 offset:7292
	s_waitcnt vmcnt(7)
	ds_write_b32 v10, v96 offset:8320
	ds_write_b32 v10, v97 offset:8324
	ds_write_b32 v10, v98 offset:8328
	ds_write_b32 v10, v99 offset:8332
	s_waitcnt vmcnt(6)
	ds_write_b32 v10, v100 offset:9360
	ds_write_b32 v10, v101 offset:9364
	ds_write_b32 v10, v102 offset:9368
	ds_write_b32 v10, v103 offset:9372
	s_waitcnt vmcnt(5)
	ds_write_b32 v10, v104 offset:10400
	ds_write_b32 v10, v105 offset:10404
	ds_write_b32 v10, v106 offset:10408
	ds_write_b32 v10, v107 offset:10412
	s_waitcnt vmcnt(4)
	ds_write_b32 v10, v108 offset:11440
	ds_write_b32 v10, v109 offset:11444
	ds_write_b32 v10, v110 offset:11448
	ds_write_b32 v10, v111 offset:11452
	s_waitcnt vmcnt(3)
	ds_write_b32 v10, v112 offset:12480
	ds_write_b32 v10, v113 offset:12484
	ds_write_b32 v10, v114 offset:12488
	ds_write_b32 v10, v115 offset:12492
	s_waitcnt vmcnt(2)
	ds_write_b32 v10, v116 offset:13520
	ds_write_b32 v10, v117 offset:13524
	ds_write_b32 v10, v118 offset:13528
	ds_write_b32 v10, v119 offset:13532
	s_waitcnt vmcnt(1)
	ds_write_b32 v10, v120 offset:14560
	ds_write_b32 v10, v121 offset:14564
	ds_write_b32 v10, v122 offset:14568
	ds_write_b32 v10, v123 offset:14572
	s_waitcnt vmcnt(0)
; __device__ __forceinline__ unsigned pk2(float lo, float hi) { return f2bf(lo) | (f2bf(hi) << 16); }
; #define LDS_WAIT() asm volatile("s_waitcnt lgkmcnt(0)" ::: "memory")
; __device__ __forceinline__ void transpose_item64(const float* __restrict__ W, int K, int N, bf16* __restrict__ WT, int mode, float* scr, int item, int lane) {
;     ...
;     const int c = lane & 7;
; #pragma unroll
;     for (int j = 0; j < 8; ++j) {
;         const int n = (lane >> 3) + 8 * j; const float* s = scr + (8 * c) * 65 + n;
;         u32x4 o; o.x = pk2(s[0], s[65]); o.y = pk2(s[2 * 65], s[3 * 65]); o.z = pk2(s[4 * 65], s[5 * 65]); o.w = pk2(s[6 * 65], s[7 * 65]);
;         const int dn = n0 + n; int row = dn; if (mode == 3) row = u_newpos(dn); else if (mode) row = ((dn >> 7) << 8) + (dn & 127) + (mode == 2 ? 128 : 0);
;         *(u32x4*)(WT + (size_t)row * K + k0 + 8 * c) = o;
;     }
;     LDS_WAIT();
	ds_write_b32 v10, v124 offset:15600
	ds_write_b32 v10, v125 offset:15604
	ds_write_b32 v10, v126 offset:15608
	ds_write_b32 v10, v127 offset:15612
	s_waitcnt lgkmcnt(0)
	ds_read2_b32 v[20:21], v11 offset0:0 offset1:65
	ds_read2_b32 v[22:23], v11 offset0:130 offset1:195
	ds_read2_b32 v[24:25], v12 offset0:0 offset1:65
	ds_read2_b32 v[26:27], v12 offset0:130 offset1:195
	ds_read2_b32 v[28:29], v11 offset0:8 offset1:73
	ds_read2_b32 v[30:31], v11 offset0:138 offset1:203
	ds_read2_b32 v[32:33], v12 offset0:8 offset1:73
	ds_read2_b32 v[34:35], v12 offset0:138 offset1:203
	s_waitcnt lgkmcnt(4)
	v_cvt_pk_bf16_f32 v36, v20, v21
	v_cvt_pk_bf16_f32 v37, v22, v23
	v_cvt_pk_bf16_f32 v38, v24, v25
	v_cvt_pk_bf16_f32 v39, v26, v27
	s_mov_b32 s22, s12
	v_lshl_add_u64 v[8:9], v[6:7], 0, s[22:23]
	global_store_dwordx4 v[8:9], v[36:39], off nt
	ds_read2_b32 v[20:21], v11 offset0:16 offset1:81
	ds_read2_b32 v[22:23], v11 offset0:146 offset1:211
	ds_read2_b32 v[24:25], v12 offset0:16 offset1:81
	ds_read2_b32 v[26:27], v12 offset0:146 offset1:211
	s_waitcnt lgkmcnt(4)
	v_cvt_pk_bf16_f32 v40, v28, v29
	v_cvt_pk_bf16_f32 v41, v30, v31
	v_cvt_pk_bf16_f32 v42, v32, v33
	v_cvt_pk_bf16_f32 v43, v34, v35
	v_lshl_add_u64 v[8:9], v[8:9], 0, s[24:25]
	global_store_dwordx4 v[8:9], v[40:43], off nt
	ds_read2_b32 v[28:29], v11 offset0:24 offset1:89
	ds_read2_b32 v[30:31], v11 offset0:154 offset1:219
	ds_read2_b32 v[32:33], v12 offset0:24 offset1:89
	ds_read2_b32 v[34:35], v12 offset0:154 offset1:219
	s_waitcnt lgkmcnt(4)
	v_cvt_pk_bf16_f32 v36, v20, v21
	v_cvt_pk_bf16_f32 v37, v22, v23
	v_cvt_pk_bf16_f32 v38, v24, v25
	v_cvt_pk_bf16_f32 v39, v26, v27
	s_mov_b32 s22, s13
	v_lshl_add_u64 v[8:9], v[6:7], 0, s[22:23]
	global_store_dwordx4 v[8:9], v[36:39], off nt
	ds_read2_b32 v[20:21], v11 offset0:32 offset1:97
	ds_read2_b32 v[22:23], v11 offset0:162 offset1:227
	ds_read2_b32 v[24:25], v12 offset0:32 offset1:97
	ds_read2_b32 v[26:27], v12 offset0:162 offset1:227
	s_waitcnt lgkmcnt(4)
	v_cvt_pk_bf16_f32 v40, v28, v29
	v_cvt_pk_bf16_f32 v41, v30, v31
	v_cvt_pk_bf16_f32 v42, v32, v33
	v_cvt_pk_bf16_f32 v43, v34, v35
	v_lshl_add_u64 v[8:9], v[8:9], 0, s[24:25]
	global_store_dwordx4 v[8:9], v[40:43], off nt
	ds_read2_b32 v[28:29], v11 offset0:40 offset1:105
	ds_read2_b32 v[30:31], v11 offset0:170 offset1:235
	ds_read2_b32 v[32:33], v12 offset0:40 offset1:105
	ds_read2_b32 v[34:35], v12 offset0:170 offset1:235
	s_waitcnt lgkmcnt(4)
	v_cvt_pk_bf16_f32 v36, v20, v21
	v_cvt_pk_bf16_f32 v37, v22, v23
	v_cvt_pk_bf16_f32 v38, v24, v25
	v_cvt_pk_bf16_f32 v39, v26, v27
	s_mov_b32 s22, s14
	v_lshl_add_u64 v[8:9], v[6:7], 0, s[22:23]
	global_store_dwordx4 v[8:9], v[36:39], off nt
	ds_read2_b32 v[20:21], v11 offset0:48 offset1:113
	ds_read2_b32 v[22:23], v11 offset0:178 offset1:243
	ds_read2_b32 v[24:25], v12 offset0:48 offset1:113
	ds_read2_b32 v[26:27], v12 offset0:178 offset1:243
	s_waitcnt lgkmcnt(4)
	v_cvt_pk_bf16_f32 v40, v28, v29
	v_cvt_pk_bf16_f32 v41, v30, v31
	v_cvt_pk_bf16_f32 v42, v32, v33
	v_cvt_pk_bf16_f32 v43, v34, v35
	v_lshl_add_u64 v[8:9], v[8:9], 0, s[24:25]
	global_store_dwordx4 v[8:9], v[40:43], off nt
	ds_read2_b32 v[28:29], v11 offset0:56 offset1:121
	ds_read2_b32 v[30:31], v11 offset0:186 offset1:251
	ds_read2_b32 v[32:33], v12 offset0:56 offset1:121
	ds_read2_b32 v[34:35], v12 offset0:186 offset1:251
	s_waitcnt lgkmcnt(4)
	v_cvt_pk_bf16_f32 v36, v20, v21
	v_cvt_pk_bf16_f32 v37, v22, v23
	v_cvt_pk_bf16_f32 v38, v24, v25
	v_cvt_pk_bf16_f32 v39, v26, v27
	s_mov_b32 s22, s15
	v_lshl_add_u64 v[8:9], v[6:7], 0, s[22:23]
	global_store_dwordx4 v[8:9], v[36:39], off nt
	s_waitcnt lgkmcnt(0)
	v_cvt_pk_bf16_f32 v40, v28, v29
	v_cvt_pk_bf16_f32 v41, v30, v31
	v_cvt_pk_bf16_f32 v42, v32, v33
	v_cvt_pk_bf16_f32 v43, v34, v35
	v_lshl_add_u64 v[8:9], v[8:9], 0, s[24:25]
	global_store_dwordx4 v[8:9], v[40:43], off nt
	s_add_u32 s18, s18, s20
	s_cmp_lt_i32 s18, s19
	s_cbranch_scc1 .Ltr_loop
